# scanA HGRN2 state MFMA re-tiled (wave = 32 permuted key rows x half of the value columns) so state stores are 16 bytes per lane
# speedup vs baseline: 1.0152x; 1.0024x over previous
.LBB0_1203:
	s_or_b64 exec, exec, s[0:1]
	v_and_b32_e32 v25, 0xffff, v2
	v_lshrrev_b32_e32 v2, 16, v2
	v_lshl_or_b32 v25, v6, 16, v25
	v_and_or_b32 v2, v6, s28, v2
	v_add_u32_e32 v6, 0x5000, v59
	ds_write2_b32 v6, v25, v2 offset1:36
	v_and_b32_e32 v2, 0xffff, v3
	v_lshrrev_b32_e32 v3, 16, v3
	v_lshl_or_b32 v2, v7, 16, v2
	v_and_or_b32 v3, v7, s28, v3
	ds_write2_b32 v6, v2, v3 offset0:72 offset1:108
	v_and_b32_e32 v2, 0xffff, v4
	v_lshrrev_b32_e32 v3, 16, v4
	v_lshl_or_b32 v2, v8, 16, v2
	v_and_or_b32 v3, v8, s28, v3
	ds_write2_b32 v6, v2, v3 offset0:144 offset1:180
	v_and_b32_e32 v2, 0xffff, v5
	v_lshrrev_b32_e32 v3, 16, v5
	v_lshl_or_b32 v2, v9, 16, v2
	v_and_or_b32 v3, v9, s28, v3
	ds_write2_b32 v6, v2, v3 offset0:216 offset1:252
	s_waitcnt lgkmcnt(0)
	s_barrier
	v_readfirstlane_b32 s98, v0
	v_and_b32_e32 v223, 15, v0
	v_bfe_u32 v224, v0, 4, 2
	s_lshr_b32 s98, s98, 6
	s_lshr_b32 s99, s98, 1
	s_and_b32 s100, s98, 1
	v_lshrrev_b32_e32 v220, 2, v223
	v_and_b32_e32 v221, 3, v223
	v_lshl_add_u32 v220, v220, 3, v221
	s_lshl_b32 s101, s99, 5
	v_add_u32_e32 v220, s101, v220
	v_mul_u32_u24_e32 v220, 0x90, v220
	v_lshl_add_u32 v220, v224, 4, v220
	s_lshl_b32 s101, s100, 6
	v_add_u32_e32 v221, s101, v223
	v_mul_u32_u24_e32 v221, 0x90, v221
	v_lshl_add_u32 v221, v224, 4, v221
	ds_read_b128 v[140:143], v220 offset:2048
	ds_read_b128 v[144:147], v220 offset:2112
	ds_read_b128 v[148:151], v220 offset:2624
	ds_read_b128 v[152:155], v220 offset:2688
	ds_read_b128 v[156:159], v221 offset:20480
	ds_read_b128 v[160:163], v221 offset:20544
	ds_read_b128 v[164:167], v221 offset:22784
	ds_read_b128 v[168:171], v221 offset:22848
	ds_read_b128 v[172:175], v221 offset:25088
	ds_read_b128 v[176:179], v221 offset:25152
	ds_read_b128 v[180:183], v221 offset:27392
	ds_read_b128 v[184:187], v221 offset:27456
	v_lshlrev_b32_e32 v222, 8, v223
	v_lshl_add_u32 v222, v224, 4, v222
	s_lshl_b32 s101, s100, 14
	v_add_u32_e32 v222, s101, v222
	s_lshl_b32 s101, s99, 6
	v_add_u32_e32 v222, s101, v222
	s_lshl_b32 s4, s16, 18
	s_lshl_b32 s5, s14, 15
	s_add_i32 s4, s4, s5
	s_add_u32 s0, s90, s4
	s_addc_u32 s1, s91, 0
	s_waitcnt lgkmcnt(6)
	v_mfma_f32_16x16x32_bf16 v[188:191], v[140:143], v[156:159], 0
	v_mfma_f32_16x16x32_bf16 v[192:195], v[148:151], v[156:159], 0
	v_mfma_f32_16x16x32_bf16 v[188:191], v[144:147], v[160:163], v[188:191]
	v_mfma_f32_16x16x32_bf16 v[192:195], v[152:155], v[160:163], v[192:195]
	s_waitcnt lgkmcnt(4)
	v_mfma_f32_16x16x32_bf16 v[196:199], v[140:143], v[164:167], 0
	v_mfma_f32_16x16x32_bf16 v[200:203], v[148:151], v[164:167], 0
	v_mfma_f32_16x16x32_bf16 v[196:199], v[144:147], v[168:171], v[196:199]
	v_mfma_f32_16x16x32_bf16 v[200:203], v[152:155], v[168:171], v[200:203]
	s_waitcnt lgkmcnt(2)
	v_mfma_f32_16x16x32_bf16 v[204:207], v[140:143], v[172:175], 0
	v_mfma_f32_16x16x32_bf16 v[208:211], v[148:151], v[172:175], 0
	v_mfma_f32_16x16x32_bf16 v[204:207], v[144:147], v[176:179], v[204:207]
	v_mfma_f32_16x16x32_bf16 v[208:211], v[152:155], v[176:179], v[208:211]
	s_waitcnt lgkmcnt(0)
	v_mfma_f32_16x16x32_bf16 v[212:215], v[140:143], v[180:183], 0
	v_mfma_f32_16x16x32_bf16 v[216:219], v[148:151], v[180:183], 0
	v_mfma_f32_16x16x32_bf16 v[212:215], v[144:147], v[184:187], v[212:215]
	v_mfma_f32_16x16x32_bf16 v[216:219], v[152:155], v[184:187], v[216:219]
	s_nop 7
	s_nop 1
	v_cvt_pk_bf16_f32 v188, v188, v189
	v_cvt_pk_bf16_f32 v189, v190, v191
	v_cvt_pk_bf16_f32 v190, v192, v193
	v_cvt_pk_bf16_f32 v191, v194, v195
	global_store_dwordx4 v222, v[188:191], s[0:1]
	v_cvt_pk_bf16_f32 v196, v196, v197
	v_cvt_pk_bf16_f32 v197, v198, v199
	v_cvt_pk_bf16_f32 v198, v200, v201
	v_cvt_pk_bf16_f32 v199, v202, v203
	v_add_u32_e32 v222, 0x1000, v222
	global_store_dwordx4 v222, v[196:199], s[0:1]
	v_cvt_pk_bf16_f32 v204, v204, v205
	v_cvt_pk_bf16_f32 v205, v206, v207
	v_cvt_pk_bf16_f32 v206, v208, v209
	v_cvt_pk_bf16_f32 v207, v210, v211
	v_add_u32_e32 v222, 0x1000, v222
	global_store_dwordx4 v222, v[204:207], s[0:1]
	v_cvt_pk_bf16_f32 v212, v212, v213
	v_cvt_pk_bf16_f32 v213, v214, v215
	v_cvt_pk_bf16_f32 v214, v216, v217
	v_cvt_pk_bf16_f32 v215, v218, v219
	v_add_u32_e32 v222, 0x1000, v222
	global_store_dwordx4 v222, v[212:215], s[0:1]
	s_waitcnt vmcnt(4)
	v_lshlrev_b32_e32 v23, 16, v122
	v_lshlrev_b32_e32 v64, 16, v123
	v_lshlrev_b32_e32 v21, 16, v129
	v_lshlrev_b32_e32 v63, 16, v128
	v_lshlrev_b32_e32 v65, 16, v127
	v_lshlrev_b32_e32 v66, 16, v124
	v_lshlrev_b32_e32 v67, 16, v126
	v_lshlrev_b32_e32 v68, 16, v125
	v_lshlrev_b32_e32 v70, 16, v130
	v_lshlrev_b32_e32 v72, 16, v131
	v_lshlrev_b32_e32 v74, 16, v132
	v_lshlrev_b32_e32 v76, 16, v133
	v_lshlrev_b32_e32 v75, 16, v134
	v_lshlrev_b32_e32 v73, 16, v135
	v_lshlrev_b32_e32 v71, 16, v136
	v_lshlrev_b32_e32 v69, 16, v137
	v_mov_b32_e32 v77, v64
	v_mov_b64_e32 v[2:3], v[10:11]
	s_waitcnt vmcnt(4)
	v_mov_b64_e32 v[6:7], v[14:15]
	s_andn2_b64 vcc, exec, s[12:13]
	v_mov_b64_e32 v[4:5], v[12:13]
	v_mov_b64_e32 v[8:9], v[16:17]
	s_mov_b32 s0, s30
	v_mov_b32_e32 v27, v21
	v_mov_b32_e32 v25, v23
	v_mov_b32_e32 v78, v63
	v_mov_b32_e32 v80, v65
	v_mov_b32_e32 v79, v66
	v_mov_b32_e32 v82, v67
	v_mov_b32_e32 v81, v68
	v_mov_b32_e32 v44, v69
	v_mov_b32_e32 v83, v70
	v_mov_b32_e32 v38, v71
	v_mov_b32_e32 v45, v72
	v_mov_b32_e32 v34, v73
	v_mov_b32_e32 v39, v74
	v_mov_b32_e32 v84, v75
	v_mov_b32_e32 v35, v76
	s_barrier
	s_cbranch_vccz .LBB0_1210
